# speedup vs baseline: 1.0375x; 1.0012x over previous
; DI unsigned pk_bf16(float lo, float hi) { unsigned r; asm("v_cvt_pk_bf16_f32 %0, %1, %2" : "=v"(r) : "v"(lo), "v"(hi)); return r; }
; DI float bf_lo(unsigned u) { return __uint_as_float(u << 16); }
; DI float bf_hi(unsigned u) { return __uint_as_float(u & 0xffff0000u); }
; DI float bf2f(bf16_t h) { return __uint_as_float((unsigned)h << 16); }
; DI bf16_t f2bf(float x) { return (bf16_t)(pk_bf16(x, 0.f) & 0xffffu); }
; DI int obid() { int b = blockIdx.x; asm volatile("" : "+s"(b)); return b; }
; DI void phase_onorm(const Params& P) {
;     ...
;     for (int row = obid() * 8 + w; row < T; row += gridDim.x * 8) {
;         const bf16_t* r = CP + (size_t)row * 448;
;         const u32x2 a = __builtin_nontemporal_load((const u32x2*)(r + 4 * lane));
;         const unsigned kvp = __builtin_nontemporal_load((const unsigned*)(r + 256 + 2 * lane));
;         const float x1 = bf2f(r[384 + (lane & 31)]), x2 = bf2f(r[416 + (lane & 31)]);
;         float q0 = bf_lo(a.x), q1 = bf_hi(a.x), q2 = bf_lo(a.y), q3 = bf_hi(a.y);
;         const float rq = rsqrtf(wave_sum(q0 * q0 + q1 * q1 + q2 * q2 + q3 * q3, lane) * (1.f / 256.f) + LN_EPS);
;         u32x2 o; o.x = pk_bf16(q0 * rq * qg[0], q1 * rq * qg[1]); o.y = pk_bf16(q2 * rq * qg[2], q3 * rq * qg[3]);
;         *(u32x2*)(CQ + (size_t)row * 256 + 4 * lane) = o;
;         const float k0 = bf_lo(kvp), k1 = bf_hi(kvp);
;         const float rk = rsqrtf(wave_sum(k0 * k0 + k1 * k1, lane) * (1.f / 128.f) + LN_EPS);
;         *(unsigned*)(CKV + (size_t)row * 256 + 2 * lane) = pk_bf16(k0 * rk * kg0, k1 * rk * kg1);
;         *(unsigned*)(CKV + (size_t)row * 256 + 128 + 2 * lane) = 0u;
;         float s, c; sincos_acc((float)P.pos[row] * fr_, s, c);
;         const float out = lane < 32 ? x1 * c - x2 * s : x2 * c + x1 * s;
;         KPE[(size_t)row * 64 + lane] = f2bf(out);
.LBB0_92:
	v_mov_b64_e32 v[18:19], s[30:31]
	s_movk_i32 s20, 0x380
	v_mad_i64_i32 v[18:19], s[26:27], v6, s20, v[18:19]
	v_lshl_add_u64 v[22:23], v[18:19], 0, v[8:9]
	flat_load_dwordx2 v[22:23], v[22:23] nt
	v_lshl_add_u64 v[24:25], v[18:19], 0, v[14:15]
	flat_load_dword v21, v[24:25] offset:512 nt
	v_lshl_add_u64 v[18:19], v[18:19], 0, v[184:185]
	flat_load_ushort v28, v[18:19] offset:768
	flat_load_ushort v29, v[18:19] offset:832
	v_ashrrev_i32_e32 v7, 31, v6
	s_movk_i32 s20, 0x7fff
	v_lshl_add_u64 v[30:31], v[6:7], 2, s[52:53]
	global_load_dword v32, v[30:31], off
	s_waitcnt vmcnt(0) lgkmcnt(0)
	v_lshlrev_b32_e32 v24, 16, v22
	v_and_b32_e32 v22, 0xffff0000, v22
	v_mul_f32_e32 v26, v22, v22
	v_lshlrev_b32_e32 v25, 16, v23
	v_fmac_f32_e32 v26, v24, v24
	v_and_b32_e32 v23, 0xffff0000, v23
	v_fmac_f32_e32 v26, v25, v25
	v_fmac_f32_e32 v26, v23, v23
	v_and_b32_e32 v19, 0xffff0000, v21
	v_lshlrev_b32_e32 v18, 16, v21
	v_add_f32_dpp v26, v26, v26 quad_perm:[1,0,3,2] row_mask:0xf bank_mask:0xf bound_ctrl:1
	v_mul_f32_e32 v21, v19, v19
	v_fmac_f32_e32 v21, v18, v18
	v_add_f32_dpp v26, v26, v26 quad_perm:[2,3,0,1] row_mask:0xf bank_mask:0xf bound_ctrl:1
	s_nop 0
	v_add_f32_dpp v21, v21, v21 quad_perm:[1,0,3,2] row_mask:0xf bank_mask:0xf bound_ctrl:1
	v_add_f32_dpp v26, v26, v26 row_half_mirror row_mask:0xf bank_mask:0xf bound_ctrl:1
	s_nop 0
	v_add_f32_dpp v21, v21, v21 quad_perm:[2,3,0,1] row_mask:0xf bank_mask:0xf bound_ctrl:1
	v_add_f32_dpp v26, v26, v26 row_mirror row_mask:0xf bank_mask:0xf bound_ctrl:1
	v_mov_b32_e32 v27, v26
	s_nop 1
	v_permlane16_swap_b32_e32 v26, v27
	v_add_f32_e32 v26, v26, v27
	v_mov_b32_e32 v27, v26
	s_nop 1
	v_permlane32_swap_b32_e32 v26, v27
	v_add_f32_e32 v26, v26, v27
	v_fmamk_f32 v26, v26, 0x3b800000, v198
	v_cmp_gt_f32_e64 s[40:41], s25, v26
	v_mul_f32_e32 v27, 0x4b800000, v26
	v_add_f32_dpp v21, v21, v21 row_half_mirror row_mask:0xf bank_mask:0xf bound_ctrl:1
	v_cndmask_b32_e64 v26, v26, v27, s[40:41]
	v_rsq_f32_e32 v26, v26
	v_add_f32_dpp v21, v21, v21 row_mirror row_mask:0xf bank_mask:0xf bound_ctrl:1
	v_mul_f32_e32 v27, 0x45800000, v26
	v_cndmask_b32_e64 v26, v26, v27, s[40:41]
	v_mul_f32_e32 v24, v26, v24
	v_mul_f32_e32 v22, v26, v22
	v_mul_f32_e32 v24, v0, v24
	v_mul_f32_e32 v22, v1, v22
	v_cvt_pk_bf16_f32 v22, v24, v22
	v_mul_f32_e32 v24, v26, v25
	v_mul_f32_e32 v23, v26, v23
	v_mul_f32_e32 v24, v2, v24
	v_mul_f32_e32 v23, v3, v23
	v_cvt_pk_bf16_f32 v23, v24, v23
	v_lshlrev_b64 v[24:25], 9, v[6:7]
	v_lshl_add_u64 v[26:27], v[10:11], 0, v[24:25]
	flat_store_dwordx2 v[26:27], v[22:23]
	v_mov_b32_e32 v22, v21
	s_nop 1
	v_permlane16_swap_b32_e32 v21, v22
	v_add_f32_e32 v21, v21, v22
	v_mov_b32_e32 v22, v21
	s_nop 1
	v_permlane32_swap_b32_e32 v21, v22
	v_add_f32_e32 v21, v21, v22
	v_fmamk_f32 v21, v21, 0x3c000000, v198
	v_cmp_gt_f32_e64 s[40:41], s25, v21
	v_mul_f32_e32 v22, 0x4b800000, v21
	v_lshlrev_b32_e32 v23, 16, v29
	v_cndmask_b32_e64 v21, v21, v22, s[40:41]
	v_rsq_f32_e32 v21, v21
	s_nop 0
	v_mul_f32_e32 v22, 0x45800000, v21
	v_cndmask_b32_e64 v21, v21, v22, s[40:41]
	v_mul_f32_e32 v18, v21, v18
	v_mul_f32_e32 v19, v21, v19
	v_mul_f32_e32 v18, v4, v18
	v_mul_f32_e32 v19, v5, v19
	v_cvt_pk_bf16_f32 v21, v18, v19
	v_lshl_add_u64 v[18:19], v[16:17], 0, v[24:25]
	flat_store_dword v[18:19], v21
	flat_store_dword v[18:19], v185 offset:256
	v_lshlrev_b32_e32 v22, 16, v28
	v_cvt_f32_i32_e32 v18, v32
	v_mul_f32_e32 v18, v20, v18
	v_mul_f32_e32 v19, 0.15915494, v18
	v_rndne_f32_e32 v19, v19
	v_fmac_f32_e32 v18, 0xc0c90fdb, v19
	v_fmac_f32_e32 v18, 0x343bbd2e, v19
	v_mul_f32_e32 v18, 0.15915494, v18
	v_sin_f32_e32 v19, v18
	v_cos_f32_e32 v18, v18
	s_nop 0
	v_pk_mul_f32 v[24:25], v[18:19], v[22:23]
	s_nop 0
	v_sub_f32_e32 v21, v24, v25
	v_mov_b32_e32 v24, v19
	v_mov_b32_e32 v25, v18
	v_pk_mul_f32 v[18:19], v[24:25], v[22:23]
	s_nop 0
	v_add_f32_e32 v18, v19, v18
	v_cndmask_b32_e32 v18, v18, v21, vcc
	v_cvt_pk_bf16_f32 v21, v18, v185
	v_lshlrev_b64 v[18:19], 7, v[6:7]
	v_add_u32_e32 v6, s70, v6
	v_cmp_lt_i32_e64 s[40:41], s20, v6
	v_lshl_add_u64 v[18:19], v[12:13], 0, v[18:19]
	s_or_b64 s[44:45], s[40:41], s[44:45]
	flat_store_short v[18:19], v21
	s_andn2_b64 exec, exec, s[44:45]
	s_cbranch_execnz .LBB0_92
